# gdn_out staging loads issued together (comb XA/XS tiles and W/QD/QK tiles) with one wait
# speedup vs baseline: 1.0441x; 1.0102x over previous
; DI unsigned pk2(float lo, float hi) { const hwf2_t v = {lo, hi}; const hwbf2_t b = __builtin_convertvector(v, hwbf2_t); return __builtin_bit_cast(unsigned, b); }
; DI float lo16(unsigned w) { return __uint_as_float(w << 16); }
; DI float hi16(unsigned w) { return __uint_as_float(w & 0xffff0000u); }
; DI void lds_barrier() { asm volatile("s_waitcnt lgkmcnt(0)" ::: "memory"); __builtin_amdgcn_s_barrier(); asm volatile("" ::: "memory"); }
; DI void gdn_out(CP c, int l, int item, unsigned char* sm) {
;     ...
;         bf16_t* As = Ws; bf16_t* S8s = (bf16_t*)OS;
; #pragma unroll
;         for (int k = 0; k < 4; ++k) { const int v = tid + 512 * k, r = v >> 4, sg = (v & 15) * 8;
;             *(u32x4*)(As + r * 136 + sg) = *(const u32x4*)(XAg + (size_t)v * 8); *(u32x4*)(S8s + r * 136 + sg) = *(const u32x4*)(XSg + (size_t)v * 8); }
;         lds_barrier();
;         bf16x8 Bf[4];
; #pragma unroll
;         for (int s2 = 0; s2 < 4; ++s2) Bf[s2] = *(const bf16x8*)(S8s + (16 * w + fr) * 136 + 32 * s2 + 8 * fq);
; #pragma unroll
;         for (int mt = 0; mt < 8; ++mt) { f32x4 a = (f32x4){0.f, 0.f, 0.f, 0.f};
; #pragma unroll
;             for (int s2 = 0; s2 < 4; ++s2) a = __builtin_amdgcn_mfma_f32_16x16x32_bf16(*(const bf16x8*)(As + (16 * mt + fr) * 136 + 32 * s2 + 8 * fq), Bf[s2], a, 0, 0, 0);
;             if (fin) { float* o = c->out + O_PGDN + ((size_t)l * 4 + hh) * 16384;
; #pragma unroll
;                 for (int i = 0; i < 4; ++i) o[(16 * mt + 4 * fq + i) * 128 + 16 * w + fr] += a[i]; }
;             else { const u32x2 bb = *(const u32x2*)(SNg + (size_t)(16 * w + fr) * 128 + 16 * mt + 4 * fq);
;                 u32x2 p; p.x = pk2(a[0] + lo16(bb.x), a[1] + hi16(bb.x)); p.y = pk2(a[2] + lo16(bb.y), a[3] + hi16(bb.y));
;                 *(u32x2*)(STs + (16 * w + fr) * 136 + 16 * mt + 4 * fq) = p; }
.LBB0_508:
	v_and_b32_e32 v34, 48, v22
	v_ashrrev_i32_e32 v30, 6, v22
	v_and_b32_e32 v32, 15, v22
	v_bfe_u32 v31, v22, 4, 2
	s_and_b32 s42, s8, 3
	s_andn2_b64 vcc, exec, s[26:27]
	v_add_u32_e32 v33, 0, v34
	s_cbranch_vccnz .LBB0_542
	s_add_i32 s14, s8, 0xfffffb80
	s_and_b64 s[24:25], s[22:23], exec
	s_cselect_b32 s26, s14, s42
	s_and_b32 s24, s8, -4
	s_or_b32 s24, s24, s42
	s_addk_i32 s24, 0xfe00
	s_and_b64 s[22:23], s[22:23], exec
	s_mov_b32 s22, 0x1c6c6000
	s_cselect_b32 s22, s22, 0x1b6c6000
	s_cselect_b32 s14, s14, s24
	s_add_u32 s24, s20, s22
	s_addc_u32 s25, s21, 0
	s_lshl_b64 s[22:23], s[14:15], 15
	s_add_u32 s24, s24, s22
	s_addc_u32 s25, s25, s23
	s_waitcnt vmcnt(0)
	v_lshlrev_b64 v[6:7], 4, v[22:23]
	v_lshl_add_u64 v[2:3], s[24:25], 0, v[6:7]
	global_load_dwordx4 v[72:75], v[2:3], off
	s_mov_b32 s14, s26
	v_and_b32_e32 v38, 0x78, v37
	s_movk_i32 s26, 0x88
	s_lshl_b64 s[22:23], s[14:15], 15
	v_lshlrev_b32_e32 v0, 1, v38
	v_mul_lo_u32 v39, v36, s26
	s_add_u32 s22, s29, s22
	v_add_u32_e32 v8, 0, v0
	v_lshlrev_b32_e32 v9, 1, v39
	s_addc_u32 s23, s30, s23
	v_add_u32_e32 v10, v8, v9
	v_readlane_b32 s27, v253, 62
	v_mul_lo_u32 v40, v35, s26
	s_movk_i32 s26, 0x110
	v_add_u32_e32 v0, s27, v0
	v_lshl_or_b32 v28, v30, 4, v32
	v_mul_lo_u32 v20, v28, s26
	v_ashrrev_i32_e32 v29, 31, v28
	v_lshlrev_b64 v[18:19], 8, v[28:29]
	v_lshl_add_u64 v[18:19], s[12:13], 0, v[18:19]
	v_mad_u32_u24 v29, v32, s26, v33
	s_and_b64 vcc, exec, s[18:19]
	v_mov_b32_e32 v104, v10
	v_lshl_add_u64 v[2:3], s[22:23], 0, v[6:7]
	global_load_dwordx4 v[76:79], v[2:3], off
	v_add_u32_e32 v6, v0, v9
	v_lshlrev_b32_e32 v9, 1, v40
	v_add_u32_e32 v10, v8, v9
	v_mov_b32_e32 v105, v6
	v_lshlrev_b64 v[6:7], 4, v[24:25]
	v_lshl_add_u64 v[2:3], s[24:25], 0, v[6:7]
	global_load_dwordx4 v[80:83], v[2:3], off
	v_mov_b32_e32 v106, v10
	v_lshl_add_u64 v[2:3], s[22:23], 0, v[6:7]
	global_load_dwordx4 v[84:87], v[2:3], off
	v_add_u32_e32 v6, v0, v9
	v_mov_b32_e32 v107, v6
	v_add_u32_e32 v2, 0x400, v22
	v_ashrrev_i32_e32 v3, 31, v2
	v_lshlrev_b64 v[6:7], 4, v[2:3]
	v_lshrrev_b32_e32 v9, 4, v2
	v_lshl_add_u64 v[2:3], s[24:25], 0, v[6:7]
	global_load_dwordx4 v[88:91], v[2:3], off
	v_mul_lo_u32 v9, v9, s26
	v_add_u32_e32 v10, v8, v9
	v_mov_b32_e32 v108, v10
	v_lshl_add_u64 v[2:3], s[22:23], 0, v[6:7]
	global_load_dwordx4 v[92:95], v[2:3], off
	v_add_u32_e32 v6, v0, v9
	v_mov_b32_e32 v109, v6
	v_add_u32_e32 v2, 0x600, v22
	v_ashrrev_i32_e32 v3, 31, v2
	v_lshlrev_b64 v[6:7], 4, v[2:3]
	v_lshrrev_b32_e32 v9, 4, v2
	v_lshl_add_u64 v[2:3], s[24:25], 0, v[6:7]
	global_load_dwordx4 v[96:99], v[2:3], off
	v_mul_lo_u32 v9, v9, s26
	v_add_u32_e32 v8, v8, v9
	v_add_u32_e32 v0, v0, v9
	s_mov_b64 s[24:25], -1
	v_lshl_add_u64 v[2:3], s[22:23], 0, v[6:7]
	global_load_dwordx4 v[100:103], v[2:3], off
	s_waitcnt vmcnt(0)
	ds_write_b128 v104, v[72:75]
	ds_write_b128 v105, v[76:79]
	ds_write_b128 v106, v[80:83]
	ds_write_b128 v107, v[84:87]
	ds_write_b128 v108, v[88:91]
	ds_write_b128 v109, v[92:95]
	ds_write_b128 v8, v[96:99]
	ds_write_b128 v0, v[100:103]
	s_waitcnt lgkmcnt(0)
	s_barrier
	v_add3_u32 v0, s27, v20, v34
	ds_read_b128 v[14:17], v0
	ds_read_b128 v[10:13], v0 offset:64
	ds_read_b128 v[6:9], v0 offset:128
	ds_read_b128 v[2:5], v0 offset:192
	v_lshlrev_b32_e32 v0, 3, v31
	v_lshl_add_u64 v[26:27], v[18:19], 0, v[0:1]
	v_add3_u32 v0, 0, v20, v0
	ds_read_b128 v[18:21], v29
	ds_read_b128 v[42:45], v29 offset:64
	s_waitcnt lgkmcnt(1)
	v_mfma_f32_16x16x32_bf16 v[18:21], v[18:21], v[14:17], 0
	s_waitcnt lgkmcnt(0)
	v_mfma_f32_16x16x32_bf16 v[18:21], v[42:45], v[10:13], v[18:21]
	ds_read_b128 v[42:45], v29 offset:128
	s_waitcnt lgkmcnt(0)
	v_mfma_f32_16x16x32_bf16 v[18:21], v[42:45], v[6:9], v[18:21]
	ds_read_b128 v[42:45], v29 offset:192
	s_waitcnt lgkmcnt(0)
	v_mfma_f32_16x16x32_bf16 v[18:21], v[42:45], v[2:5], v[18:21]
	s_cbranch_vccz .LBB0_511
	global_load_dwordx2 v[42:43], v[26:27], off
	s_mov_b64 s[24:25], 0
	s_waitcnt vmcnt(0)
	v_lshlrev_b32_e32 v44, 16, v42
	v_and_b32_e32 v45, 0xffff0000, v42
	s_nop 1
	v_pk_add_f32 v[44:45], v[18:19], v[44:45]
	s_nop 0
	v_cvt_pk_bf16_f32 v42, v44, v45
	v_lshlrev_b32_e32 v44, 16, v43
	v_and_b32_e32 v45, 0xffff0000, v43
	v_pk_add_f32 v[44:45], v[20:21], v[44:45]
	s_nop 0
	v_cvt_pk_bf16_f32 v43, v44, v45
	ds_write_b64 v0, v[42:43] offset:62464

; DI void gdn_out(CP c, int l, int item, unsigned char* sm) {
;     ...
; #pragma unroll
;     for (int k = 0; k < 2; ++k) { const int v = tid + 512 * k, r = v >> 4, sg = (v & 15) * 8;
;         *(u32x4*)(Ws + r * 136 + sg) = *(const u32x4*)(Wg + (size_t)v * 8); *(u32x4*)(QDs + r * 136 + sg) = *(const u32x4*)(QDg + (size_t)v * 8); }
;     { const int v = tid, r = v >> 3, sg = (v & 7) * 8; *(u32x4*)(QKs + r * 72 + sg) = *(const u32x4*)(QKg + (size_t)v * 8); }
;     if (!comb) {
; #pragma unroll
;         for (int k = 0; k < 4; ++k) { const int v = tid + 512 * k, r = v >> 4, sg = (v & 15) * 8; *(u32x4*)(STs + r * 136 + sg) = *(const u32x4*)(SNg + (size_t)v * 8); }
;     }
.LBB0_542:
	s_and_b64 vcc, exec, s[24:25]
	s_cbranch_vccz .LBB0_505
	s_xor_b64 s[16:17], s[16:17], -1
	s_add_u32 s18, s20, s0
	s_addc_u32 s19, s21, s1
	s_waitcnt vmcnt(0)
	v_lshl_add_u64 v[4:5], v[4:5], 1, s[18:19]
	v_add_co_u32_e32 v10, vcc, 0x156c4000, v4
	v_lshl_add_u32 v0, v38, 1, 0
	s_nop 0
	v_addc_co_u32_e32 v11, vcc, 0, v5, vcc
	global_load_dwordx4 v[72:75], v[10:11], off
	v_add_co_u32_e32 v4, vcc, 0x168c4000, v4
	v_lshl_add_u32 v9, v39, 1, v0
	s_nop 0
	v_addc_co_u32_e32 v5, vcc, 0, v5, vcc
	s_movk_i32 s14, 0x90
	global_load_dwordx4 v[76:79], v[4:5], off
	v_mov_b32_e32 v70, v9
	v_lshl_add_u64 v[10:11], v[2:3], 1, s[18:19]
	v_add_co_u32_e32 v2, vcc, 0x156c4000, v10
	v_lshl_add_u32 v9, v40, 1, v0
	s_nop 0
	v_addc_co_u32_e32 v3, vcc, 0, v11, vcc
	global_load_dwordx4 v[80:83], v[2:3], off
	s_add_u32 s18, s20, s6
	s_addc_u32 s19, s21, s7
	v_and_b32_e32 v13, 56, v8
	v_lshrrev_b32_e32 v12, 3, v22
	v_add_co_u32_e32 v2, vcc, 0x168c4000, v10
	s_nop 1
	v_addc_co_u32_e32 v3, vcc, 0, v11, vcc
	global_load_dwordx4 v[84:87], v[2:3], off
	s_andn2_b64 vcc, exec, s[16:17]
	v_lshlrev_b64 v[2:3], 4, v[22:23]
	v_lshl_add_u64 v[4:5], s[18:19], 0, v[2:3]
	global_load_dwordx4 v[88:91], v[4:5], off
	v_mul_lo_u32 v4, v12, s14
	v_lshlrev_b32_e32 v5, 1, v13
	v_add3_u32 v4, 0, v4, v5
	s_waitcnt vmcnt(0)
	ds_write_b128 v70, v[72:75]
	ds_write_b128 v70, v[76:79] offset:17408
	ds_write_b128 v9, v[80:83]
	ds_write_b128 v9, v[84:87] offset:17408
	ds_write_b128 v4, v[88:91] offset:34816
	s_cbranch_vccnz .LBB0_545
	v_lshl_add_u64 v[8:9], v[24:25], 4, s[12:13]
	v_add_u32_e32 v20, 0x400, v22
	v_add_u32_e32 v24, 0x600, v22
	v_ashrrev_i32_e32 v21, 31, v20
	v_ashrrev_i32_e32 v25, 31, v24
	v_lshl_add_u64 v[2:3], s[12:13], 0, v[2:3]
	v_lshl_add_u64 v[12:13], v[20:21], 4, s[12:13]
	v_lshl_add_u64 v[16:17], v[24:25], 4, s[12:13]
	global_load_dwordx4 v[2:5], v[2:3], off
	s_nop 0
	global_load_dwordx4 v[8:11], v[8:9], off
	s_nop 0
	global_load_dwordx4 v[12:15], v[12:13], off
	s_nop 0
	global_load_dwordx4 v[16:19], v[16:17], off
	s_movk_i32 s14, 0x110
	v_mad_u64_u32 v[26:27], s[12:13], v6, s14, v[0:1]
	v_mad_u64_u32 v[6:7], s[12:13], v7, s14, v[0:1]
	v_lshrrev_b32_e32 v7, 4, v20
	v_lshrrev_b32_e32 v23, 4, v24
	v_mad_u64_u32 v[20:21], s[12:13], v7, s14, v[0:1]
	v_mad_u64_u32 v[24:25], s[12:13], v23, s14, v[0:1]
	s_waitcnt vmcnt(3)
	ds_write_b128 v26, v[2:5] offset:62464
	s_waitcnt vmcnt(2)
	ds_write_b128 v6, v[8:11] offset:62464
	s_waitcnt vmcnt(1)
	ds_write_b128 v20, v[12:15] offset:62464
	s_waitcnt vmcnt(0)
	ds_write_b128 v24, v[16:19] offset:62464
